# hand-written conformer conv phase (DPP LayerNorm, 2 barriers per unit, counted LDS read pipeline) on top of gMLP + attention store widening
# speedup vs baseline: 1.0530x; 1.0058x over previous
.LBB0_491:
	s_mov_b64 exec, -1
	s_barrier
	s_cmpk_gt_i32 s2, 0x3ff
	s_cbranch_scc1 .LBB0_546
	v_and_b32_e32 v0, 63, v181
	v_lshrrev_b32_e32 v10, 6, v181
	v_and_b32_e32 v1, 0xff, v181
	v_lshlrev_b32_e32 v6, 4, v181
	v_readfirstlane_b32 s0, v10
	v_lshlrev_b32_e32 v7, 4, v0
	v_mov_b32_e32 v8, 0x3b000000
	v_mov_b32_e32 v9, 0x3727c5ac
	v_mov_b32_e32 v11, 0xbfb8aa3b
	v_mov_b32_e32 v13, 1.0
	s_nop 3
	s_lshr_b32 s1, s0, 2
	s_add_u32 s8, s64, 0x6200000
	s_addc_u32 s9, s65, 0
	s_add_u32 s10, s64, 0xe200400
	s_addc_u32 s11, s65, 0
	s_lshl_b32 s4, s1, 14
	v_lshl_add_u32 v2, v1, 2, s4
	s_lshl_b32 s4, s1, 15
	s_add_i32 s4, s4, 0xf800
	v_lshl_add_u32 v4, v1, 3, s4
	s_lshl_b32 s4, s0, 13
	s_add_i32 s4, s4, 0xf800
	v_lshl_add_u32 v5, v0, 5, s4
	v_lshlrev_b32_e32 v10, 3, v1
	s_mov_b64 s[28:29], s[52:53]
	global_load_dwordx2 v[16:17], v10, s[28:29] offset:0
	global_load_dwordx2 v[18:19], v10, s[28:29] offset:2048
	s_add_u32 s28, s28, 0x1000
	s_addc_u32 s29, s29, 0
	global_load_dwordx2 v[20:21], v10, s[28:29] offset:0
	global_load_dwordx2 v[22:23], v10, s[28:29] offset:2048
	s_add_u32 s28, s28, 0x1000
	s_addc_u32 s29, s29, 0
	global_load_dwordx2 v[24:25], v10, s[28:29] offset:0
	global_load_dwordx2 v[26:27], v10, s[28:29] offset:2048
	s_add_u32 s28, s28, 0x1000
	s_addc_u32 s29, s29, 0
	global_load_dwordx2 v[28:29], v10, s[28:29] offset:0
	global_load_dwordx2 v[30:31], v10, s[28:29] offset:2048
	s_add_u32 s28, s28, 0x1000
	s_addc_u32 s29, s29, 0
	global_load_dwordx2 v[32:33], v10, s[28:29] offset:0
	global_load_dwordx2 v[34:35], v10, s[28:29] offset:2048
	s_add_u32 s28, s28, 0x1000
	s_addc_u32 s29, s29, 0
	global_load_dwordx2 v[36:37], v10, s[28:29] offset:0
	global_load_dwordx2 v[38:39], v10, s[28:29] offset:2048
	s_add_u32 s28, s28, 0x1000
	s_addc_u32 s29, s29, 0
	global_load_dwordx2 v[40:41], v10, s[28:29] offset:0
	global_load_dwordx2 v[42:43], v10, s[28:29] offset:2048
	s_add_u32 s28, s28, 0x1000
	s_addc_u32 s29, s29, 0
	global_load_dwordx2 v[44:45], v10, s[28:29] offset:0
	global_load_dwordx2 v[46:47], v10, s[28:29] offset:2048
	s_add_u32 s28, s28, 0x1000
	s_addc_u32 s29, s29, 0
	global_load_dwordx2 v[48:49], v10, s[28:29] offset:0
	global_load_dwordx2 v[50:51], v10, s[28:29] offset:2048
	s_add_u32 s28, s28, 0x1000
	s_addc_u32 s29, s29, 0
	global_load_dwordx2 v[52:53], v10, s[28:29] offset:0
	global_load_dwordx2 v[54:55], v10, s[28:29] offset:2048
	s_add_u32 s28, s28, 0x1000
	s_addc_u32 s29, s29, 0
	global_load_dwordx2 v[56:57], v10, s[28:29] offset:0
	global_load_dwordx2 v[58:59], v10, s[28:29] offset:2048
	s_add_u32 s28, s28, 0x1000
	s_addc_u32 s29, s29, 0
	global_load_dwordx2 v[60:61], v10, s[28:29] offset:0
	global_load_dwordx2 v[62:63], v10, s[28:29] offset:2048
	s_add_u32 s28, s28, 0x1000
	s_addc_u32 s29, s29, 0
	global_load_dwordx2 v[64:65], v10, s[28:29] offset:0
	global_load_dwordx2 v[66:67], v10, s[28:29] offset:2048
	s_add_u32 s28, s28, 0x1000
	s_addc_u32 s29, s29, 0
	global_load_dwordx2 v[68:69], v10, s[28:29] offset:0
	global_load_dwordx2 v[70:71], v10, s[28:29] offset:2048
	s_add_u32 s28, s28, 0x1000
	s_addc_u32 s29, s29, 0
	global_load_dwordx2 v[72:73], v10, s[28:29] offset:0
	global_load_dwordx2 v[74:75], v10, s[28:29] offset:2048
	s_add_u32 s28, s28, 0x1000
	s_addc_u32 s29, s29, 0
	global_load_dwordx2 v[76:77], v10, s[28:29] offset:0
	global_load_dwordx2 v[78:79], v10, s[54:55]
	v_lshlrev_b32_e32 v12, 5, v0
	global_load_dwordx4 v[224:227], v12, s[56:57]
	global_load_dwordx4 v[228:231], v12, s[56:57] offset:16
	global_load_dwordx4 v[232:235], v12, s[58:59]
	global_load_dwordx4 v[236:239], v12, s[58:59] offset:16
	s_mov_b32 s12, s2
	s_lshl_b32 s4, s12, 15
	s_add_u32 s28, s8, s4
	s_addc_u32 s29, s9, 0
	s_sub_u32 s28, s28, 0x7800
	s_subb_u32 s29, s29, 0
	s_add_u32 s30, s28, 0x2000
	s_addc_u32 s31, s29, 0
	s_and_b32 s4, s12, 0xff
	s_cmp_eq_u32 s4, 0
	s_cbranch_scc1 .Lcv_fz0
	global_load_dwordx4 v[112:115], v6, s[28:29]
	s_add_u32 s28, s28, 0x4000
	s_addc_u32 s29, s29, 0
	global_load_dwordx4 v[116:119], v6, s[30:31]
	s_add_u32 s30, s30, 0x4000
	s_addc_u32 s31, s31, 0
	global_load_dwordx4 v[120:123], v6, s[28:29]
	s_add_u32 s28, s28, 0x4000
	s_addc_u32 s29, s29, 0
	global_load_dwordx4 v[124:127], v6, s[30:31]
	s_add_u32 s30, s30, 0x4000
	s_addc_u32 s31, s31, 0
	global_load_dwordx4 v[128:131], v6, s[28:29]
	s_add_u32 s28, s28, 0x4000
	s_addc_u32 s29, s29, 0
	global_load_dwordx4 v[132:135], v6, s[30:31]
	s_add_u32 s30, s30, 0x4000
	s_addc_u32 s31, s31, 0
	global_load_dwordx4 v[136:139], v6, s[28:29]
	s_cmp_lt_u32 s0, 6
	s_cbranch_scc0 .Lcv_fd0
	global_load_dwordx4 v[140:143], v6, s[30:31]
	s_branch .Lcv_fd0
.Lcv_fz0:
	v_mov_b32_e32 v112, 0
	v_mov_b32_e32 v113, 0
	v_mov_b32_e32 v114, 0
	v_mov_b32_e32 v115, 0
	v_mov_b32_e32 v116, 0
	v_mov_b32_e32 v117, 0
	v_mov_b32_e32 v118, 0
	v_mov_b32_e32 v119, 0
	v_mov_b32_e32 v120, 0
	v_mov_b32_e32 v121, 0
	v_mov_b32_e32 v122, 0
	v_mov_b32_e32 v123, 0
	s_add_u32 s28, s28, 0x8000
	s_addc_u32 s29, s29, 0
	s_add_u32 s30, s30, 0x4000
	s_addc_u32 s31, s31, 0
	s_cmp_lt_u32 s0, 6
	s_cbranch_scc0 .Lcv_fzl0
	v_mov_b32_e32 v124, 0
	v_mov_b32_e32 v125, 0
	v_mov_b32_e32 v126, 0
	v_mov_b32_e32 v127, 0
	s_branch .Lcv_fzm0
.Lcv_fzl0:
	global_load_dwordx4 v[124:127], v6, s[30:31]
.Lcv_fzm0:
	s_add_u32 s30, s30, 0x4000
	s_addc_u32 s31, s31, 0
	global_load_dwordx4 v[128:131], v6, s[28:29]
	global_load_dwordx4 v[132:135], v6, s[30:31]
	s_add_u32 s28, s28, 0x4000
	s_addc_u32 s29, s29, 0
	s_add_u32 s30, s30, 0x4000
	s_addc_u32 s31, s31, 0
	global_load_dwordx4 v[136:139], v6, s[28:29]
	s_cmp_lt_u32 s0, 6
	s_cbranch_scc0 .Lcv_fd0
	global_load_dwordx4 v[140:143], v6, s[30:31]

.Lcv_loop:
	s_waitcnt vmcnt(4)
	ds_write_b128 v6, v[112:115] offset:0
	ds_write_b128 v6, v[116:119] offset:8192
	ds_write_b128 v6, v[120:123] offset:16384
	ds_write_b128 v6, v[124:127] offset:24576
	ds_write_b128 v6, v[128:131] offset:32768
	ds_write_b128 v6, v[132:135] offset:40960
	ds_write_b128 v6, v[136:139] offset:49152
	s_cmp_lt_u32 s0, 6
	s_cbranch_scc0 .Lcv_c7
	ds_write_b128 v6, v[140:143] offset:57344
.Lcv_c7:
	s_waitcnt lgkmcnt(0)
	s_barrier
	s_add_i32 s23, s12, s66
	s_cmp_lt_i32 s23, 0x400
	s_cbranch_scc0 .Lcv_nofetch
	s_lshl_b32 s4, s23, 15
	s_add_u32 s28, s8, s4
	s_addc_u32 s29, s9, 0
	s_sub_u32 s28, s28, 0x7800
	s_subb_u32 s29, s29, 0
	s_add_u32 s30, s28, 0x2000
	s_addc_u32 s31, s29, 0
	s_and_b32 s4, s23, 0xff
	s_cmp_eq_u32 s4, 0
	s_cbranch_scc1 .Lcv_fz1
	global_load_dwordx4 v[112:115], v6, s[28:29]
	s_add_u32 s28, s28, 0x4000
	s_addc_u32 s29, s29, 0
	global_load_dwordx4 v[116:119], v6, s[30:31]
	s_add_u32 s30, s30, 0x4000
	s_addc_u32 s31, s31, 0
	global_load_dwordx4 v[120:123], v6, s[28:29]
	s_add_u32 s28, s28, 0x4000
	s_addc_u32 s29, s29, 0
	global_load_dwordx4 v[124:127], v6, s[30:31]
	s_add_u32 s30, s30, 0x4000
	s_addc_u32 s31, s31, 0
	global_load_dwordx4 v[128:131], v6, s[28:29]
	s_add_u32 s28, s28, 0x4000
	s_addc_u32 s29, s29, 0
	global_load_dwordx4 v[132:135], v6, s[30:31]
	s_add_u32 s30, s30, 0x4000
	s_addc_u32 s31, s31, 0
	global_load_dwordx4 v[136:139], v6, s[28:29]
	s_cmp_lt_u32 s0, 6
	s_cbranch_scc0 .Lcv_fd1
	global_load_dwordx4 v[140:143], v6, s[30:31]
	s_branch .Lcv_fd1

.Lcv_fd1:
.Lcv_nofetch:
	v_mov_b32_e32 v80, v78
	v_mov_b32_e32 v81, v79
	v_mov_b32_e32 v82, v78
	v_mov_b32_e32 v83, v79
	v_mov_b32_e32 v84, v78
	v_mov_b32_e32 v85, v79
	v_mov_b32_e32 v86, v78
	v_mov_b32_e32 v87, v79
	v_mov_b32_e32 v88, v78
	v_mov_b32_e32 v89, v79
	v_mov_b32_e32 v90, v78
	v_mov_b32_e32 v91, v79
	v_mov_b32_e32 v92, v78
	v_mov_b32_e32 v93, v79
	v_mov_b32_e32 v94, v78
	v_mov_b32_e32 v95, v79
	v_mov_b32_e32 v96, v78
	v_mov_b32_e32 v97, v79
	v_mov_b32_e32 v98, v78
	v_mov_b32_e32 v99, v79
	v_mov_b32_e32 v100, v78
	v_mov_b32_e32 v101, v79
	v_mov_b32_e32 v102, v78
	v_mov_b32_e32 v103, v79
	v_mov_b32_e32 v104, v78
	v_mov_b32_e32 v105, v79
	v_mov_b32_e32 v106, v78
	v_mov_b32_e32 v107, v79
	v_mov_b32_e32 v108, v78
	v_mov_b32_e32 v109, v79
	v_mov_b32_e32 v110, v78
	v_mov_b32_e32 v111, v79
	ds_read_b32 v144, v2 offset:0
	ds_read_b32 v145, v2 offset:1024
	ds_read_b32 v146, v2 offset:2048
	ds_read_b32 v147, v2 offset:3072
	ds_read_b32 v148, v2 offset:4096
	ds_read_b32 v149, v2 offset:5120
	ds_read_b32 v150, v2 offset:6144
	ds_read_b32 v151, v2 offset:7168
	ds_read_b32 v152, v2 offset:8192
	ds_read_b32 v153, v2 offset:9216
	ds_read_b32 v154, v2 offset:10240
	ds_read_b32 v155, v2 offset:11264
	ds_read_b32 v156, v2 offset:12288
	s_waitcnt lgkmcnt(12)
	v_lshlrev_b32_e32 v204, 16, v144
	v_and_b32_e32 v205, 0xffff0000, v144
	v_pk_fma_f32 v[80:81], v[16:17], v[204:205], v[80:81]
	ds_read_b32 v157, v2 offset:13312
	s_waitcnt lgkmcnt(12)
	v_lshlrev_b32_e32 v204, 16, v145
	v_and_b32_e32 v205, 0xffff0000, v145
	v_pk_fma_f32 v[80:81], v[18:19], v[204:205], v[80:81]
	v_pk_fma_f32 v[82:83], v[16:17], v[204:205], v[82:83]
	ds_read_b32 v158, v2 offset:14336
	s_waitcnt lgkmcnt(12)
	v_lshlrev_b32_e32 v204, 16, v146
	v_and_b32_e32 v205, 0xffff0000, v146
	v_pk_fma_f32 v[80:81], v[20:21], v[204:205], v[80:81]
	v_pk_fma_f32 v[82:83], v[18:19], v[204:205], v[82:83]
	v_pk_fma_f32 v[84:85], v[16:17], v[204:205], v[84:85]
	ds_read_b32 v159, v2 offset:15360
	s_waitcnt lgkmcnt(12)
	v_lshlrev_b32_e32 v204, 16, v147
	v_and_b32_e32 v205, 0xffff0000, v147
	v_pk_fma_f32 v[80:81], v[22:23], v[204:205], v[80:81]
	v_pk_fma_f32 v[82:83], v[20:21], v[204:205], v[82:83]
	v_pk_fma_f32 v[84:85], v[18:19], v[204:205], v[84:85]
	v_pk_fma_f32 v[86:87], v[16:17], v[204:205], v[86:87]
	ds_read_b32 v160, v2 offset:16384
	s_waitcnt lgkmcnt(12)
	v_lshlrev_b32_e32 v204, 16, v148
	v_and_b32_e32 v205, 0xffff0000, v148
	v_pk_fma_f32 v[80:81], v[24:25], v[204:205], v[80:81]
	v_pk_fma_f32 v[82:83], v[22:23], v[204:205], v[82:83]
	v_pk_fma_f32 v[84:85], v[20:21], v[204:205], v[84:85]
	v_pk_fma_f32 v[86:87], v[18:19], v[204:205], v[86:87]
	v_pk_fma_f32 v[88:89], v[16:17], v[204:205], v[88:89]
	ds_read_b32 v161, v2 offset:17408
	s_waitcnt lgkmcnt(12)
	v_lshlrev_b32_e32 v204, 16, v149
	v_and_b32_e32 v205, 0xffff0000, v149
	v_pk_fma_f32 v[80:81], v[26:27], v[204:205], v[80:81]
	v_pk_fma_f32 v[82:83], v[24:25], v[204:205], v[82:83]
	v_pk_fma_f32 v[84:85], v[22:23], v[204:205], v[84:85]
	v_pk_fma_f32 v[86:87], v[20:21], v[204:205], v[86:87]
	v_pk_fma_f32 v[88:89], v[18:19], v[204:205], v[88:89]
	v_pk_fma_f32 v[90:91], v[16:17], v[204:205], v[90:91]
	ds_read_b32 v162, v2 offset:18432
	s_waitcnt lgkmcnt(12)
	v_lshlrev_b32_e32 v204, 16, v150
	v_and_b32_e32 v205, 0xffff0000, v150
	v_pk_fma_f32 v[80:81], v[28:29], v[204:205], v[80:81]
	v_pk_fma_f32 v[82:83], v[26:27], v[204:205], v[82:83]
	v_pk_fma_f32 v[84:85], v[24:25], v[204:205], v[84:85]
	v_pk_fma_f32 v[86:87], v[22:23], v[204:205], v[86:87]
	v_pk_fma_f32 v[88:89], v[20:21], v[204:205], v[88:89]
	v_pk_fma_f32 v[90:91], v[18:19], v[204:205], v[90:91]
	v_pk_fma_f32 v[92:93], v[16:17], v[204:205], v[92:93]
	ds_read_b32 v163, v2 offset:19456
	s_waitcnt lgkmcnt(12)
	v_lshlrev_b32_e32 v204, 16, v151
	v_and_b32_e32 v205, 0xffff0000, v151
	v_pk_fma_f32 v[80:81], v[30:31], v[204:205], v[80:81]
	v_pk_fma_f32 v[82:83], v[28:29], v[204:205], v[82:83]
	v_pk_fma_f32 v[84:85], v[26:27], v[204:205], v[84:85]
	v_pk_fma_f32 v[86:87], v[24:25], v[204:205], v[86:87]
	v_pk_fma_f32 v[88:89], v[22:23], v[204:205], v[88:89]
	v_pk_fma_f32 v[90:91], v[20:21], v[204:205], v[90:91]
	v_pk_fma_f32 v[92:93], v[18:19], v[204:205], v[92:93]
	v_pk_fma_f32 v[94:95], v[16:17], v[204:205], v[94:95]
	ds_read_b32 v164, v2 offset:20480
	s_waitcnt lgkmcnt(12)
	v_lshlrev_b32_e32 v204, 16, v152
	v_and_b32_e32 v205, 0xffff0000, v152
	v_pk_fma_f32 v[80:81], v[32:33], v[204:205], v[80:81]
	v_pk_fma_f32 v[82:83], v[30:31], v[204:205], v[82:83]
	v_pk_fma_f32 v[84:85], v[28:29], v[204:205], v[84:85]
	v_pk_fma_f32 v[86:87], v[26:27], v[204:205], v[86:87]
	v_pk_fma_f32 v[88:89], v[24:25], v[204:205], v[88:89]
	v_pk_fma_f32 v[90:91], v[22:23], v[204:205], v[90:91]
	v_pk_fma_f32 v[92:93], v[20:21], v[204:205], v[92:93]
	v_pk_fma_f32 v[94:95], v[18:19], v[204:205], v[94:95]
	v_pk_fma_f32 v[96:97], v[16:17], v[204:205], v[96:97]
	ds_read_b32 v165, v2 offset:21504
	s_waitcnt lgkmcnt(12)
	v_lshlrev_b32_e32 v204, 16, v153
	v_and_b32_e32 v205, 0xffff0000, v153
	v_pk_fma_f32 v[80:81], v[34:35], v[204:205], v[80:81]
	v_pk_fma_f32 v[82:83], v[32:33], v[204:205], v[82:83]
	v_pk_fma_f32 v[84:85], v[30:31], v[204:205], v[84:85]
	v_pk_fma_f32 v[86:87], v[28:29], v[204:205], v[86:87]
	v_pk_fma_f32 v[88:89], v[26:27], v[204:205], v[88:89]
	v_pk_fma_f32 v[90:91], v[24:25], v[204:205], v[90:91]
	v_pk_fma_f32 v[92:93], v[22:23], v[204:205], v[92:93]
	v_pk_fma_f32 v[94:95], v[20:21], v[204:205], v[94:95]
	v_pk_fma_f32 v[96:97], v[18:19], v[204:205], v[96:97]
	v_pk_fma_f32 v[98:99], v[16:17], v[204:205], v[98:99]
	ds_read_b32 v166, v2 offset:22528
	s_waitcnt lgkmcnt(12)
	v_lshlrev_b32_e32 v204, 16, v154
	v_and_b32_e32 v205, 0xffff0000, v154
	v_pk_fma_f32 v[80:81], v[36:37], v[204:205], v[80:81]
	v_pk_fma_f32 v[82:83], v[34:35], v[204:205], v[82:83]
	v_pk_fma_f32 v[84:85], v[32:33], v[204:205], v[84:85]
	v_pk_fma_f32 v[86:87], v[30:31], v[204:205], v[86:87]
	v_pk_fma_f32 v[88:89], v[28:29], v[204:205], v[88:89]
	v_pk_fma_f32 v[90:91], v[26:27], v[204:205], v[90:91]
	v_pk_fma_f32 v[92:93], v[24:25], v[204:205], v[92:93]
	v_pk_fma_f32 v[94:95], v[22:23], v[204:205], v[94:95]
	v_pk_fma_f32 v[96:97], v[20:21], v[204:205], v[96:97]
	v_pk_fma_f32 v[98:99], v[18:19], v[204:205], v[98:99]
	v_pk_fma_f32 v[100:101], v[16:17], v[204:205], v[100:101]
	ds_read_b32 v167, v2 offset:23552
	s_waitcnt lgkmcnt(12)
	v_lshlrev_b32_e32 v204, 16, v155
	v_and_b32_e32 v205, 0xffff0000, v155
	v_pk_fma_f32 v[80:81], v[38:39], v[204:205], v[80:81]
	v_pk_fma_f32 v[82:83], v[36:37], v[204:205], v[82:83]
	v_pk_fma_f32 v[84:85], v[34:35], v[204:205], v[84:85]
	v_pk_fma_f32 v[86:87], v[32:33], v[204:205], v[86:87]
	v_pk_fma_f32 v[88:89], v[30:31], v[204:205], v[88:89]
	v_pk_fma_f32 v[90:91], v[28:29], v[204:205], v[90:91]
	v_pk_fma_f32 v[92:93], v[26:27], v[204:205], v[92:93]
	v_pk_fma_f32 v[94:95], v[24:25], v[204:205], v[94:95]
	v_pk_fma_f32 v[96:97], v[22:23], v[204:205], v[96:97]
	v_pk_fma_f32 v[98:99], v[20:21], v[204:205], v[98:99]
	v_pk_fma_f32 v[100:101], v[18:19], v[204:205], v[100:101]
	v_pk_fma_f32 v[102:103], v[16:17], v[204:205], v[102:103]
	ds_read_b32 v168, v2 offset:24576
	s_waitcnt lgkmcnt(12)
	v_lshlrev_b32_e32 v204, 16, v156
	v_and_b32_e32 v205, 0xffff0000, v156
	v_pk_fma_f32 v[80:81], v[40:41], v[204:205], v[80:81]
	v_pk_fma_f32 v[82:83], v[38:39], v[204:205], v[82:83]
	v_pk_fma_f32 v[84:85], v[36:37], v[204:205], v[84:85]
	v_pk_fma_f32 v[86:87], v[34:35], v[204:205], v[86:87]
	v_pk_fma_f32 v[88:89], v[32:33], v[204:205], v[88:89]
	v_pk_fma_f32 v[90:91], v[30:31], v[204:205], v[90:91]
	v_pk_fma_f32 v[92:93], v[28:29], v[204:205], v[92:93]
	v_pk_fma_f32 v[94:95], v[26:27], v[204:205], v[94:95]
	v_pk_fma_f32 v[96:97], v[24:25], v[204:205], v[96:97]
	v_pk_fma_f32 v[98:99], v[22:23], v[204:205], v[98:99]
	v_pk_fma_f32 v[100:101], v[20:21], v[204:205], v[100:101]
	v_pk_fma_f32 v[102:103], v[18:19], v[204:205], v[102:103]
	v_pk_fma_f32 v[104:105], v[16:17], v[204:205], v[104:105]
	ds_read_b32 v169, v2 offset:25600
	s_waitcnt lgkmcnt(12)
	v_lshlrev_b32_e32 v204, 16, v157
	v_and_b32_e32 v205, 0xffff0000, v157
	v_pk_fma_f32 v[80:81], v[42:43], v[204:205], v[80:81]
	v_pk_fma_f32 v[82:83], v[40:41], v[204:205], v[82:83]
	v_pk_fma_f32 v[84:85], v[38:39], v[204:205], v[84:85]
	v_pk_fma_f32 v[86:87], v[36:37], v[204:205], v[86:87]
	v_pk_fma_f32 v[88:89], v[34:35], v[204:205], v[88:89]
	v_pk_fma_f32 v[90:91], v[32:33], v[204:205], v[90:91]
	v_pk_fma_f32 v[92:93], v[30:31], v[204:205], v[92:93]
	v_pk_fma_f32 v[94:95], v[28:29], v[204:205], v[94:95]
	v_pk_fma_f32 v[96:97], v[26:27], v[204:205], v[96:97]
	v_pk_fma_f32 v[98:99], v[24:25], v[204:205], v[98:99]
	v_pk_fma_f32 v[100:101], v[22:23], v[204:205], v[100:101]
	v_pk_fma_f32 v[102:103], v[20:21], v[204:205], v[102:103]
	v_pk_fma_f32 v[104:105], v[18:19], v[204:205], v[104:105]
	v_pk_fma_f32 v[106:107], v[16:17], v[204:205], v[106:107]
	ds_read_b32 v170, v2 offset:26624
	s_waitcnt lgkmcnt(12)
	v_lshlrev_b32_e32 v204, 16, v158
	v_and_b32_e32 v205, 0xffff0000, v158
	v_pk_fma_f32 v[80:81], v[44:45], v[204:205], v[80:81]
	v_pk_fma_f32 v[82:83], v[42:43], v[204:205], v[82:83]
	v_pk_fma_f32 v[84:85], v[40:41], v[204:205], v[84:85]
	v_pk_fma_f32 v[86:87], v[38:39], v[204:205], v[86:87]
	v_pk_fma_f32 v[88:89], v[36:37], v[204:205], v[88:89]
	v_pk_fma_f32 v[90:91], v[34:35], v[204:205], v[90:91]
	v_pk_fma_f32 v[92:93], v[32:33], v[204:205], v[92:93]
	v_pk_fma_f32 v[94:95], v[30:31], v[204:205], v[94:95]
	v_pk_fma_f32 v[96:97], v[28:29], v[204:205], v[96:97]
	v_pk_fma_f32 v[98:99], v[26:27], v[204:205], v[98:99]
	v_pk_fma_f32 v[100:101], v[24:25], v[204:205], v[100:101]
	v_pk_fma_f32 v[102:103], v[22:23], v[204:205], v[102:103]
	v_pk_fma_f32 v[104:105], v[20:21], v[204:205], v[104:105]
	v_pk_fma_f32 v[106:107], v[18:19], v[204:205], v[106:107]
	v_pk_fma_f32 v[108:109], v[16:17], v[204:205], v[108:109]
	ds_read_b32 v171, v2 offset:27648
	s_waitcnt lgkmcnt(12)
	v_lshlrev_b32_e32 v204, 16, v159
	v_and_b32_e32 v205, 0xffff0000, v159
	v_pk_fma_f32 v[80:81], v[46:47], v[204:205], v[80:81]
	v_pk_fma_f32 v[82:83], v[44:45], v[204:205], v[82:83]
	v_pk_fma_f32 v[84:85], v[42:43], v[204:205], v[84:85]
	v_pk_fma_f32 v[86:87], v[40:41], v[204:205], v[86:87]
	v_pk_fma_f32 v[88:89], v[38:39], v[204:205], v[88:89]
	v_pk_fma_f32 v[90:91], v[36:37], v[204:205], v[90:91]
	v_pk_fma_f32 v[92:93], v[34:35], v[204:205], v[92:93]
	v_pk_fma_f32 v[94:95], v[32:33], v[204:205], v[94:95]
	v_pk_fma_f32 v[96:97], v[30:31], v[204:205], v[96:97]
	v_pk_fma_f32 v[98:99], v[28:29], v[204:205], v[98:99]
	v_pk_fma_f32 v[100:101], v[26:27], v[204:205], v[100:101]
	v_pk_fma_f32 v[102:103], v[24:25], v[204:205], v[102:103]
	v_pk_fma_f32 v[104:105], v[22:23], v[204:205], v[104:105]
	v_pk_fma_f32 v[106:107], v[20:21], v[204:205], v[106:107]
	v_pk_fma_f32 v[108:109], v[18:19], v[204:205], v[108:109]
	v_pk_fma_f32 v[110:111], v[16:17], v[204:205], v[110:111]
	ds_read_b32 v172, v2 offset:28672
	s_waitcnt lgkmcnt(12)
	v_lshlrev_b32_e32 v204, 16, v160
	v_and_b32_e32 v205, 0xffff0000, v160
	v_pk_fma_f32 v[80:81], v[48:49], v[204:205], v[80:81]
	v_pk_fma_f32 v[82:83], v[46:47], v[204:205], v[82:83]
	v_pk_fma_f32 v[84:85], v[44:45], v[204:205], v[84:85]
	v_pk_fma_f32 v[86:87], v[42:43], v[204:205], v[86:87]
	v_pk_fma_f32 v[88:89], v[40:41], v[204:205], v[88:89]
	v_pk_fma_f32 v[90:91], v[38:39], v[204:205], v[90:91]
	v_pk_fma_f32 v[92:93], v[36:37], v[204:205], v[92:93]
	v_pk_fma_f32 v[94:95], v[34:35], v[204:205], v[94:95]
	v_pk_fma_f32 v[96:97], v[32:33], v[204:205], v[96:97]
	v_pk_fma_f32 v[98:99], v[30:31], v[204:205], v[98:99]
	v_pk_fma_f32 v[100:101], v[28:29], v[204:205], v[100:101]
	v_pk_fma_f32 v[102:103], v[26:27], v[204:205], v[102:103]
	v_pk_fma_f32 v[104:105], v[24:25], v[204:205], v[104:105]
	v_pk_fma_f32 v[106:107], v[22:23], v[204:205], v[106:107]
	v_pk_fma_f32 v[108:109], v[20:21], v[204:205], v[108:109]
	v_pk_fma_f32 v[110:111], v[18:19], v[204:205], v[110:111]
	ds_read_b32 v173, v2 offset:29696
	s_waitcnt lgkmcnt(12)
	v_lshlrev_b32_e32 v204, 16, v161
	v_and_b32_e32 v205, 0xffff0000, v161
	v_pk_fma_f32 v[80:81], v[50:51], v[204:205], v[80:81]
	v_pk_fma_f32 v[82:83], v[48:49], v[204:205], v[82:83]
	v_pk_fma_f32 v[84:85], v[46:47], v[204:205], v[84:85]
	v_pk_fma_f32 v[86:87], v[44:45], v[204:205], v[86:87]
	v_pk_fma_f32 v[88:89], v[42:43], v[204:205], v[88:89]
	v_pk_fma_f32 v[90:91], v[40:41], v[204:205], v[90:91]
	v_pk_fma_f32 v[92:93], v[38:39], v[204:205], v[92:93]
	v_pk_fma_f32 v[94:95], v[36:37], v[204:205], v[94:95]
	v_pk_fma_f32 v[96:97], v[34:35], v[204:205], v[96:97]
	v_pk_fma_f32 v[98:99], v[32:33], v[204:205], v[98:99]
	v_pk_fma_f32 v[100:101], v[30:31], v[204:205], v[100:101]
	v_pk_fma_f32 v[102:103], v[28:29], v[204:205], v[102:103]
	v_pk_fma_f32 v[104:105], v[26:27], v[204:205], v[104:105]
	v_pk_fma_f32 v[106:107], v[24:25], v[204:205], v[106:107]
	v_pk_fma_f32 v[108:109], v[22:23], v[204:205], v[108:109]
	v_pk_fma_f32 v[110:111], v[20:21], v[204:205], v[110:111]
	ds_read_b32 v174, v2 offset:30720
	s_waitcnt lgkmcnt(12)
	v_lshlrev_b32_e32 v204, 16, v162
	v_and_b32_e32 v205, 0xffff0000, v162
	v_pk_fma_f32 v[80:81], v[52:53], v[204:205], v[80:81]
	v_pk_fma_f32 v[82:83], v[50:51], v[204:205], v[82:83]
	v_pk_fma_f32 v[84:85], v[48:49], v[204:205], v[84:85]
	v_pk_fma_f32 v[86:87], v[46:47], v[204:205], v[86:87]
	v_pk_fma_f32 v[88:89], v[44:45], v[204:205], v[88:89]
	v_pk_fma_f32 v[90:91], v[42:43], v[204:205], v[90:91]
	v_pk_fma_f32 v[92:93], v[40:41], v[204:205], v[92:93]
	v_pk_fma_f32 v[94:95], v[38:39], v[204:205], v[94:95]
	v_pk_fma_f32 v[96:97], v[36:37], v[204:205], v[96:97]
	v_pk_fma_f32 v[98:99], v[34:35], v[204:205], v[98:99]
	v_pk_fma_f32 v[100:101], v[32:33], v[204:205], v[100:101]
	v_pk_fma_f32 v[102:103], v[30:31], v[204:205], v[102:103]
	v_pk_fma_f32 v[104:105], v[28:29], v[204:205], v[104:105]
	v_pk_fma_f32 v[106:107], v[26:27], v[204:205], v[106:107]
	v_pk_fma_f32 v[108:109], v[24:25], v[204:205], v[108:109]
	v_pk_fma_f32 v[110:111], v[22:23], v[204:205], v[110:111]
	ds_read_b32 v175, v2 offset:31744
	s_waitcnt lgkmcnt(12)
	v_lshlrev_b32_e32 v204, 16, v163
	v_and_b32_e32 v205, 0xffff0000, v163
	v_pk_fma_f32 v[80:81], v[54:55], v[204:205], v[80:81]
	v_pk_fma_f32 v[82:83], v[52:53], v[204:205], v[82:83]
	v_pk_fma_f32 v[84:85], v[50:51], v[204:205], v[84:85]
	v_pk_fma_f32 v[86:87], v[48:49], v[204:205], v[86:87]
	v_pk_fma_f32 v[88:89], v[46:47], v[204:205], v[88:89]
	v_pk_fma_f32 v[90:91], v[44:45], v[204:205], v[90:91]
	v_pk_fma_f32 v[92:93], v[42:43], v[204:205], v[92:93]
	v_pk_fma_f32 v[94:95], v[40:41], v[204:205], v[94:95]
	v_pk_fma_f32 v[96:97], v[38:39], v[204:205], v[96:97]
	v_pk_fma_f32 v[98:99], v[36:37], v[204:205], v[98:99]
	v_pk_fma_f32 v[100:101], v[34:35], v[204:205], v[100:101]
	v_pk_fma_f32 v[102:103], v[32:33], v[204:205], v[102:103]
	v_pk_fma_f32 v[104:105], v[30:31], v[204:205], v[104:105]
	v_pk_fma_f32 v[106:107], v[28:29], v[204:205], v[106:107]
	v_pk_fma_f32 v[108:109], v[26:27], v[204:205], v[108:109]
	v_pk_fma_f32 v[110:111], v[24:25], v[204:205], v[110:111]
	ds_read_b32 v176, v2 offset:32768
	s_waitcnt lgkmcnt(12)
	v_lshlrev_b32_e32 v204, 16, v164
	v_and_b32_e32 v205, 0xffff0000, v164
	v_pk_fma_f32 v[80:81], v[56:57], v[204:205], v[80:81]
	v_pk_fma_f32 v[82:83], v[54:55], v[204:205], v[82:83]
	v_pk_fma_f32 v[84:85], v[52:53], v[204:205], v[84:85]
	v_pk_fma_f32 v[86:87], v[50:51], v[204:205], v[86:87]
	v_pk_fma_f32 v[88:89], v[48:49], v[204:205], v[88:89]
	v_pk_fma_f32 v[90:91], v[46:47], v[204:205], v[90:91]
	v_pk_fma_f32 v[92:93], v[44:45], v[204:205], v[92:93]
	v_pk_fma_f32 v[94:95], v[42:43], v[204:205], v[94:95]
	v_pk_fma_f32 v[96:97], v[40:41], v[204:205], v[96:97]
	v_pk_fma_f32 v[98:99], v[38:39], v[204:205], v[98:99]
	v_pk_fma_f32 v[100:101], v[36:37], v[204:205], v[100:101]
	v_pk_fma_f32 v[102:103], v[34:35], v[204:205], v[102:103]
	v_pk_fma_f32 v[104:105], v[32:33], v[204:205], v[104:105]
	v_pk_fma_f32 v[106:107], v[30:31], v[204:205], v[106:107]
	v_pk_fma_f32 v[108:109], v[28:29], v[204:205], v[108:109]
	v_pk_fma_f32 v[110:111], v[26:27], v[204:205], v[110:111]
	ds_read_b32 v177, v2 offset:33792
	s_waitcnt lgkmcnt(12)
	v_lshlrev_b32_e32 v204, 16, v165
	v_and_b32_e32 v205, 0xffff0000, v165
	v_pk_fma_f32 v[80:81], v[58:59], v[204:205], v[80:81]
	v_pk_fma_f32 v[82:83], v[56:57], v[204:205], v[82:83]
	v_pk_fma_f32 v[84:85], v[54:55], v[204:205], v[84:85]
	v_pk_fma_f32 v[86:87], v[52:53], v[204:205], v[86:87]
	v_pk_fma_f32 v[88:89], v[50:51], v[204:205], v[88:89]
	v_pk_fma_f32 v[90:91], v[48:49], v[204:205], v[90:91]
	v_pk_fma_f32 v[92:93], v[46:47], v[204:205], v[92:93]
	v_pk_fma_f32 v[94:95], v[44:45], v[204:205], v[94:95]
	v_pk_fma_f32 v[96:97], v[42:43], v[204:205], v[96:97]
	v_pk_fma_f32 v[98:99], v[40:41], v[204:205], v[98:99]
	v_pk_fma_f32 v[100:101], v[38:39], v[204:205], v[100:101]
	v_pk_fma_f32 v[102:103], v[36:37], v[204:205], v[102:103]
	v_pk_fma_f32 v[104:105], v[34:35], v[204:205], v[104:105]
	v_pk_fma_f32 v[106:107], v[32:33], v[204:205], v[106:107]
	v_pk_fma_f32 v[108:109], v[30:31], v[204:205], v[108:109]
	v_pk_fma_f32 v[110:111], v[28:29], v[204:205], v[110:111]
	ds_read_b32 v178, v2 offset:34816
	s_waitcnt lgkmcnt(12)
	v_lshlrev_b32_e32 v204, 16, v166
	v_and_b32_e32 v205, 0xffff0000, v166
	v_pk_fma_f32 v[80:81], v[60:61], v[204:205], v[80:81]
	v_pk_fma_f32 v[82:83], v[58:59], v[204:205], v[82:83]
	v_pk_fma_f32 v[84:85], v[56:57], v[204:205], v[84:85]
	v_pk_fma_f32 v[86:87], v[54:55], v[204:205], v[86:87]
	v_pk_fma_f32 v[88:89], v[52:53], v[204:205], v[88:89]
	v_pk_fma_f32 v[90:91], v[50:51], v[204:205], v[90:91]
	v_pk_fma_f32 v[92:93], v[48:49], v[204:205], v[92:93]
	v_pk_fma_f32 v[94:95], v[46:47], v[204:205], v[94:95]
	v_pk_fma_f32 v[96:97], v[44:45], v[204:205], v[96:97]
	v_pk_fma_f32 v[98:99], v[42:43], v[204:205], v[98:99]
	v_pk_fma_f32 v[100:101], v[40:41], v[204:205], v[100:101]
	v_pk_fma_f32 v[102:103], v[38:39], v[204:205], v[102:103]
	v_pk_fma_f32 v[104:105], v[36:37], v[204:205], v[104:105]
	v_pk_fma_f32 v[106:107], v[34:35], v[204:205], v[106:107]
	v_pk_fma_f32 v[108:109], v[32:33], v[204:205], v[108:109]
	v_pk_fma_f32 v[110:111], v[30:31], v[204:205], v[110:111]
	ds_read_b32 v179, v2 offset:35840
	s_waitcnt lgkmcnt(12)
	v_lshlrev_b32_e32 v204, 16, v167
	v_and_b32_e32 v205, 0xffff0000, v167
	v_pk_fma_f32 v[80:81], v[62:63], v[204:205], v[80:81]
	v_pk_fma_f32 v[82:83], v[60:61], v[204:205], v[82:83]
	v_pk_fma_f32 v[84:85], v[58:59], v[204:205], v[84:85]
	v_pk_fma_f32 v[86:87], v[56:57], v[204:205], v[86:87]
	v_pk_fma_f32 v[88:89], v[54:55], v[204:205], v[88:89]
	v_pk_fma_f32 v[90:91], v[52:53], v[204:205], v[90:91]
	v_pk_fma_f32 v[92:93], v[50:51], v[204:205], v[92:93]
	v_pk_fma_f32 v[94:95], v[48:49], v[204:205], v[94:95]
	v_pk_fma_f32 v[96:97], v[46:47], v[204:205], v[96:97]
	v_pk_fma_f32 v[98:99], v[44:45], v[204:205], v[98:99]
	v_pk_fma_f32 v[100:101], v[42:43], v[204:205], v[100:101]
	v_pk_fma_f32 v[102:103], v[40:41], v[204:205], v[102:103]
	v_pk_fma_f32 v[104:105], v[38:39], v[204:205], v[104:105]
	v_pk_fma_f32 v[106:107], v[36:37], v[204:205], v[106:107]
	v_pk_fma_f32 v[108:109], v[34:35], v[204:205], v[108:109]
	v_pk_fma_f32 v[110:111], v[32:33], v[204:205], v[110:111]
	ds_read_b32 v180, v2 offset:36864
	s_waitcnt lgkmcnt(12)
	v_lshlrev_b32_e32 v204, 16, v168
	v_and_b32_e32 v205, 0xffff0000, v168
	v_pk_fma_f32 v[80:81], v[64:65], v[204:205], v[80:81]
	v_pk_fma_f32 v[82:83], v[62:63], v[204:205], v[82:83]
	v_pk_fma_f32 v[84:85], v[60:61], v[204:205], v[84:85]
	v_pk_fma_f32 v[86:87], v[58:59], v[204:205], v[86:87]
	v_pk_fma_f32 v[88:89], v[56:57], v[204:205], v[88:89]
	v_pk_fma_f32 v[90:91], v[54:55], v[204:205], v[90:91]
	v_pk_fma_f32 v[92:93], v[52:53], v[204:205], v[92:93]
	v_pk_fma_f32 v[94:95], v[50:51], v[204:205], v[94:95]
	v_pk_fma_f32 v[96:97], v[48:49], v[204:205], v[96:97]
	v_pk_fma_f32 v[98:99], v[46:47], v[204:205], v[98:99]
	v_pk_fma_f32 v[100:101], v[44:45], v[204:205], v[100:101]
	v_pk_fma_f32 v[102:103], v[42:43], v[204:205], v[102:103]
	v_pk_fma_f32 v[104:105], v[40:41], v[204:205], v[104:105]
	v_pk_fma_f32 v[106:107], v[38:39], v[204:205], v[106:107]
	v_pk_fma_f32 v[108:109], v[36:37], v[204:205], v[108:109]
	v_pk_fma_f32 v[110:111], v[34:35], v[204:205], v[110:111]
	ds_read_b32 v184, v2 offset:37888
	s_waitcnt lgkmcnt(12)
	v_lshlrev_b32_e32 v204, 16, v169
	v_and_b32_e32 v205, 0xffff0000, v169
	v_pk_fma_f32 v[80:81], v[66:67], v[204:205], v[80:81]
	v_pk_fma_f32 v[82:83], v[64:65], v[204:205], v[82:83]
	v_pk_fma_f32 v[84:85], v[62:63], v[204:205], v[84:85]
	v_pk_fma_f32 v[86:87], v[60:61], v[204:205], v[86:87]
	v_pk_fma_f32 v[88:89], v[58:59], v[204:205], v[88:89]
	v_pk_fma_f32 v[90:91], v[56:57], v[204:205], v[90:91]
	v_pk_fma_f32 v[92:93], v[54:55], v[204:205], v[92:93]
	v_pk_fma_f32 v[94:95], v[52:53], v[204:205], v[94:95]
	v_pk_fma_f32 v[96:97], v[50:51], v[204:205], v[96:97]
	v_pk_fma_f32 v[98:99], v[48:49], v[204:205], v[98:99]
	v_pk_fma_f32 v[100:101], v[46:47], v[204:205], v[100:101]
	v_pk_fma_f32 v[102:103], v[44:45], v[204:205], v[102:103]
	v_pk_fma_f32 v[104:105], v[42:43], v[204:205], v[104:105]
	v_pk_fma_f32 v[106:107], v[40:41], v[204:205], v[106:107]
	v_pk_fma_f32 v[108:109], v[38:39], v[204:205], v[108:109]
	v_pk_fma_f32 v[110:111], v[36:37], v[204:205], v[110:111]
	ds_read_b32 v185, v2 offset:38912
	s_waitcnt lgkmcnt(12)
	v_lshlrev_b32_e32 v204, 16, v170
	v_and_b32_e32 v205, 0xffff0000, v170
	v_pk_fma_f32 v[80:81], v[68:69], v[204:205], v[80:81]
	v_pk_fma_f32 v[82:83], v[66:67], v[204:205], v[82:83]
	v_pk_fma_f32 v[84:85], v[64:65], v[204:205], v[84:85]
	v_pk_fma_f32 v[86:87], v[62:63], v[204:205], v[86:87]
	v_pk_fma_f32 v[88:89], v[60:61], v[204:205], v[88:89]
	v_pk_fma_f32 v[90:91], v[58:59], v[204:205], v[90:91]
	v_pk_fma_f32 v[92:93], v[56:57], v[204:205], v[92:93]
	v_pk_fma_f32 v[94:95], v[54:55], v[204:205], v[94:95]
	v_pk_fma_f32 v[96:97], v[52:53], v[204:205], v[96:97]
	v_pk_fma_f32 v[98:99], v[50:51], v[204:205], v[98:99]
	v_pk_fma_f32 v[100:101], v[48:49], v[204:205], v[100:101]
	v_pk_fma_f32 v[102:103], v[46:47], v[204:205], v[102:103]
	v_pk_fma_f32 v[104:105], v[44:45], v[204:205], v[104:105]
	v_pk_fma_f32 v[106:107], v[42:43], v[204:205], v[106:107]
	v_pk_fma_f32 v[108:109], v[40:41], v[204:205], v[108:109]
	v_pk_fma_f32 v[110:111], v[38:39], v[204:205], v[110:111]
	ds_read_b32 v186, v2 offset:39936
	s_waitcnt lgkmcnt(12)
	v_lshlrev_b32_e32 v204, 16, v171
	v_and_b32_e32 v205, 0xffff0000, v171
	v_pk_fma_f32 v[80:81], v[70:71], v[204:205], v[80:81]
	v_pk_fma_f32 v[82:83], v[68:69], v[204:205], v[82:83]
	v_pk_fma_f32 v[84:85], v[66:67], v[204:205], v[84:85]
	v_pk_fma_f32 v[86:87], v[64:65], v[204:205], v[86:87]
	v_pk_fma_f32 v[88:89], v[62:63], v[204:205], v[88:89]
	v_pk_fma_f32 v[90:91], v[60:61], v[204:205], v[90:91]
	v_pk_fma_f32 v[92:93], v[58:59], v[204:205], v[92:93]
	v_pk_fma_f32 v[94:95], v[56:57], v[204:205], v[94:95]
	v_pk_fma_f32 v[96:97], v[54:55], v[204:205], v[96:97]
	v_pk_fma_f32 v[98:99], v[52:53], v[204:205], v[98:99]
	v_pk_fma_f32 v[100:101], v[50:51], v[204:205], v[100:101]
	v_pk_fma_f32 v[102:103], v[48:49], v[204:205], v[102:103]
	v_pk_fma_f32 v[104:105], v[46:47], v[204:205], v[104:105]
	v_pk_fma_f32 v[106:107], v[44:45], v[204:205], v[106:107]
	v_pk_fma_f32 v[108:109], v[42:43], v[204:205], v[108:109]
	v_pk_fma_f32 v[110:111], v[40:41], v[204:205], v[110:111]
	ds_read_b32 v187, v2 offset:40960
	s_waitcnt lgkmcnt(12)
	v_lshlrev_b32_e32 v204, 16, v172
	v_and_b32_e32 v205, 0xffff0000, v172
	v_pk_fma_f32 v[80:81], v[72:73], v[204:205], v[80:81]
	v_pk_fma_f32 v[82:83], v[70:71], v[204:205], v[82:83]
	v_pk_fma_f32 v[84:85], v[68:69], v[204:205], v[84:85]
	v_pk_fma_f32 v[86:87], v[66:67], v[204:205], v[86:87]
	v_pk_fma_f32 v[88:89], v[64:65], v[204:205], v[88:89]
	v_pk_fma_f32 v[90:91], v[62:63], v[204:205], v[90:91]
	v_pk_fma_f32 v[92:93], v[60:61], v[204:205], v[92:93]
	v_pk_fma_f32 v[94:95], v[58:59], v[204:205], v[94:95]
	v_pk_fma_f32 v[96:97], v[56:57], v[204:205], v[96:97]
	v_pk_fma_f32 v[98:99], v[54:55], v[204:205], v[98:99]
	v_pk_fma_f32 v[100:101], v[52:53], v[204:205], v[100:101]
	v_pk_fma_f32 v[102:103], v[50:51], v[204:205], v[102:103]
	v_pk_fma_f32 v[104:105], v[48:49], v[204:205], v[104:105]
	v_pk_fma_f32 v[106:107], v[46:47], v[204:205], v[106:107]
	v_pk_fma_f32 v[108:109], v[44:45], v[204:205], v[108:109]
	v_pk_fma_f32 v[110:111], v[42:43], v[204:205], v[110:111]
	ds_read_b32 v188, v2 offset:41984
	s_waitcnt lgkmcnt(12)
	v_lshlrev_b32_e32 v204, 16, v173
	v_and_b32_e32 v205, 0xffff0000, v173
	v_pk_fma_f32 v[80:81], v[74:75], v[204:205], v[80:81]
	v_pk_fma_f32 v[82:83], v[72:73], v[204:205], v[82:83]
	v_pk_fma_f32 v[84:85], v[70:71], v[204:205], v[84:85]
	v_pk_fma_f32 v[86:87], v[68:69], v[204:205], v[86:87]
	v_pk_fma_f32 v[88:89], v[66:67], v[204:205], v[88:89]
	v_pk_fma_f32 v[90:91], v[64:65], v[204:205], v[90:91]
	v_pk_fma_f32 v[92:93], v[62:63], v[204:205], v[92:93]
	v_pk_fma_f32 v[94:95], v[60:61], v[204:205], v[94:95]
	v_pk_fma_f32 v[96:97], v[58:59], v[204:205], v[96:97]
	v_pk_fma_f32 v[98:99], v[56:57], v[204:205], v[98:99]
	v_pk_fma_f32 v[100:101], v[54:55], v[204:205], v[100:101]
	v_pk_fma_f32 v[102:103], v[52:53], v[204:205], v[102:103]
	v_pk_fma_f32 v[104:105], v[50:51], v[204:205], v[104:105]
	v_pk_fma_f32 v[106:107], v[48:49], v[204:205], v[106:107]
	v_pk_fma_f32 v[108:109], v[46:47], v[204:205], v[108:109]
	v_pk_fma_f32 v[110:111], v[44:45], v[204:205], v[110:111]
	ds_read_b32 v189, v2 offset:43008
	s_waitcnt lgkmcnt(12)
	v_lshlrev_b32_e32 v204, 16, v174
	v_and_b32_e32 v205, 0xffff0000, v174
	v_pk_fma_f32 v[80:81], v[76:77], v[204:205], v[80:81]
	v_pk_fma_f32 v[82:83], v[74:75], v[204:205], v[82:83]
	v_pk_fma_f32 v[84:85], v[72:73], v[204:205], v[84:85]
	v_pk_fma_f32 v[86:87], v[70:71], v[204:205], v[86:87]
	v_pk_fma_f32 v[88:89], v[68:69], v[204:205], v[88:89]
	v_pk_fma_f32 v[90:91], v[66:67], v[204:205], v[90:91]
	v_pk_fma_f32 v[92:93], v[64:65], v[204:205], v[92:93]
	v_pk_fma_f32 v[94:95], v[62:63], v[204:205], v[94:95]
	v_pk_fma_f32 v[96:97], v[60:61], v[204:205], v[96:97]
	v_pk_fma_f32 v[98:99], v[58:59], v[204:205], v[98:99]
	v_pk_fma_f32 v[100:101], v[56:57], v[204:205], v[100:101]
	v_pk_fma_f32 v[102:103], v[54:55], v[204:205], v[102:103]
	v_pk_fma_f32 v[104:105], v[52:53], v[204:205], v[104:105]
	v_pk_fma_f32 v[106:107], v[50:51], v[204:205], v[106:107]
	v_pk_fma_f32 v[108:109], v[48:49], v[204:205], v[108:109]
	v_pk_fma_f32 v[110:111], v[46:47], v[204:205], v[110:111]
	ds_read_b32 v190, v2 offset:44032
	s_waitcnt lgkmcnt(12)
	v_lshlrev_b32_e32 v204, 16, v175
	v_and_b32_e32 v205, 0xffff0000, v175
	v_pk_fma_f32 v[82:83], v[76:77], v[204:205], v[82:83]
	v_pk_fma_f32 v[84:85], v[74:75], v[204:205], v[84:85]
	v_pk_fma_f32 v[86:87], v[72:73], v[204:205], v[86:87]
	v_pk_fma_f32 v[88:89], v[70:71], v[204:205], v[88:89]
	v_pk_fma_f32 v[90:91], v[68:69], v[204:205], v[90:91]
	v_pk_fma_f32 v[92:93], v[66:67], v[204:205], v[92:93]
	v_pk_fma_f32 v[94:95], v[64:65], v[204:205], v[94:95]
	v_pk_fma_f32 v[96:97], v[62:63], v[204:205], v[96:97]
	v_pk_fma_f32 v[98:99], v[60:61], v[204:205], v[98:99]
	v_pk_fma_f32 v[100:101], v[58:59], v[204:205], v[100:101]
	v_pk_fma_f32 v[102:103], v[56:57], v[204:205], v[102:103]
	v_pk_fma_f32 v[104:105], v[54:55], v[204:205], v[104:105]
	v_pk_fma_f32 v[106:107], v[52:53], v[204:205], v[106:107]
	v_pk_fma_f32 v[108:109], v[50:51], v[204:205], v[108:109]
	v_pk_fma_f32 v[110:111], v[48:49], v[204:205], v[110:111]
	ds_read_b32 v191, v2 offset:45056
	s_waitcnt lgkmcnt(12)
	v_lshlrev_b32_e32 v204, 16, v176
	v_and_b32_e32 v205, 0xffff0000, v176
	v_pk_fma_f32 v[84:85], v[76:77], v[204:205], v[84:85]
	v_pk_fma_f32 v[86:87], v[74:75], v[204:205], v[86:87]
	v_pk_fma_f32 v[88:89], v[72:73], v[204:205], v[88:89]
	v_pk_fma_f32 v[90:91], v[70:71], v[204:205], v[90:91]
	v_pk_fma_f32 v[92:93], v[68:69], v[204:205], v[92:93]
	v_pk_fma_f32 v[94:95], v[66:67], v[204:205], v[94:95]
	v_pk_fma_f32 v[96:97], v[64:65], v[204:205], v[96:97]
	v_pk_fma_f32 v[98:99], v[62:63], v[204:205], v[98:99]
	v_pk_fma_f32 v[100:101], v[60:61], v[204:205], v[100:101]
	v_pk_fma_f32 v[102:103], v[58:59], v[204:205], v[102:103]
	v_pk_fma_f32 v[104:105], v[56:57], v[204:205], v[104:105]
	v_pk_fma_f32 v[106:107], v[54:55], v[204:205], v[106:107]
	v_pk_fma_f32 v[108:109], v[52:53], v[204:205], v[108:109]
	v_pk_fma_f32 v[110:111], v[50:51], v[204:205], v[110:111]
	ds_read_b32 v192, v2 offset:46080
	s_waitcnt lgkmcnt(12)
	v_lshlrev_b32_e32 v204, 16, v177
	v_and_b32_e32 v205, 0xffff0000, v177
	v_pk_fma_f32 v[86:87], v[76:77], v[204:205], v[86:87]
	v_pk_fma_f32 v[88:89], v[74:75], v[204:205], v[88:89]
	v_pk_fma_f32 v[90:91], v[72:73], v[204:205], v[90:91]
	v_pk_fma_f32 v[92:93], v[70:71], v[204:205], v[92:93]
	v_pk_fma_f32 v[94:95], v[68:69], v[204:205], v[94:95]
	v_pk_fma_f32 v[96:97], v[66:67], v[204:205], v[96:97]
	v_pk_fma_f32 v[98:99], v[64:65], v[204:205], v[98:99]
	v_pk_fma_f32 v[100:101], v[62:63], v[204:205], v[100:101]
	v_pk_fma_f32 v[102:103], v[60:61], v[204:205], v[102:103]
	v_pk_fma_f32 v[104:105], v[58:59], v[204:205], v[104:105]
	v_pk_fma_f32 v[106:107], v[56:57], v[204:205], v[106:107]
	v_pk_fma_f32 v[108:109], v[54:55], v[204:205], v[108:109]
	v_pk_fma_f32 v[110:111], v[52:53], v[204:205], v[110:111]
	s_waitcnt lgkmcnt(11)
	v_lshlrev_b32_e32 v204, 16, v178
	v_and_b32_e32 v205, 0xffff0000, v178
	v_pk_fma_f32 v[88:89], v[76:77], v[204:205], v[88:89]
	v_pk_fma_f32 v[90:91], v[74:75], v[204:205], v[90:91]
	v_pk_fma_f32 v[92:93], v[72:73], v[204:205], v[92:93]
	v_pk_fma_f32 v[94:95], v[70:71], v[204:205], v[94:95]
	v_pk_fma_f32 v[96:97], v[68:69], v[204:205], v[96:97]
	v_pk_fma_f32 v[98:99], v[66:67], v[204:205], v[98:99]
	v_pk_fma_f32 v[100:101], v[64:65], v[204:205], v[100:101]
	v_pk_fma_f32 v[102:103], v[62:63], v[204:205], v[102:103]
	v_pk_fma_f32 v[104:105], v[60:61], v[204:205], v[104:105]
	v_pk_fma_f32 v[106:107], v[58:59], v[204:205], v[106:107]
	v_pk_fma_f32 v[108:109], v[56:57], v[204:205], v[108:109]
	v_pk_fma_f32 v[110:111], v[54:55], v[204:205], v[110:111]
	s_waitcnt lgkmcnt(10)
	v_lshlrev_b32_e32 v204, 16, v179
	v_and_b32_e32 v205, 0xffff0000, v179
	v_pk_fma_f32 v[90:91], v[76:77], v[204:205], v[90:91]
	v_pk_fma_f32 v[92:93], v[74:75], v[204:205], v[92:93]
	v_pk_fma_f32 v[94:95], v[72:73], v[204:205], v[94:95]
	v_pk_fma_f32 v[96:97], v[70:71], v[204:205], v[96:97]
	v_pk_fma_f32 v[98:99], v[68:69], v[204:205], v[98:99]
	v_pk_fma_f32 v[100:101], v[66:67], v[204:205], v[100:101]
	v_pk_fma_f32 v[102:103], v[64:65], v[204:205], v[102:103]
	v_pk_fma_f32 v[104:105], v[62:63], v[204:205], v[104:105]
	v_pk_fma_f32 v[106:107], v[60:61], v[204:205], v[106:107]
	v_pk_fma_f32 v[108:109], v[58:59], v[204:205], v[108:109]
	v_pk_fma_f32 v[110:111], v[56:57], v[204:205], v[110:111]
	s_waitcnt lgkmcnt(9)
	v_lshlrev_b32_e32 v204, 16, v180
	v_and_b32_e32 v205, 0xffff0000, v180
	v_pk_fma_f32 v[92:93], v[76:77], v[204:205], v[92:93]
	v_pk_fma_f32 v[94:95], v[74:75], v[204:205], v[94:95]
	v_pk_fma_f32 v[96:97], v[72:73], v[204:205], v[96:97]
	v_pk_fma_f32 v[98:99], v[70:71], v[204:205], v[98:99]
	v_pk_fma_f32 v[100:101], v[68:69], v[204:205], v[100:101]
	v_pk_fma_f32 v[102:103], v[66:67], v[204:205], v[102:103]
	v_pk_fma_f32 v[104:105], v[64:65], v[204:205], v[104:105]
	v_pk_fma_f32 v[106:107], v[62:63], v[204:205], v[106:107]
	v_pk_fma_f32 v[108:109], v[60:61], v[204:205], v[108:109]
	v_pk_fma_f32 v[110:111], v[58:59], v[204:205], v[110:111]
	s_waitcnt lgkmcnt(8)
	v_lshlrev_b32_e32 v204, 16, v184
	v_and_b32_e32 v205, 0xffff0000, v184
	v_pk_fma_f32 v[94:95], v[76:77], v[204:205], v[94:95]
	v_pk_fma_f32 v[96:97], v[74:75], v[204:205], v[96:97]
	v_pk_fma_f32 v[98:99], v[72:73], v[204:205], v[98:99]
	v_pk_fma_f32 v[100:101], v[70:71], v[204:205], v[100:101]
	v_pk_fma_f32 v[102:103], v[68:69], v[204:205], v[102:103]
	v_pk_fma_f32 v[104:105], v[66:67], v[204:205], v[104:105]
	v_pk_fma_f32 v[106:107], v[64:65], v[204:205], v[106:107]
	v_pk_fma_f32 v[108:109], v[62:63], v[204:205], v[108:109]
	v_pk_fma_f32 v[110:111], v[60:61], v[204:205], v[110:111]
	s_waitcnt lgkmcnt(7)
	v_lshlrev_b32_e32 v204, 16, v185
	v_and_b32_e32 v205, 0xffff0000, v185
	v_pk_fma_f32 v[96:97], v[76:77], v[204:205], v[96:97]
	v_pk_fma_f32 v[98:99], v[74:75], v[204:205], v[98:99]
	v_pk_fma_f32 v[100:101], v[72:73], v[204:205], v[100:101]
	v_pk_fma_f32 v[102:103], v[70:71], v[204:205], v[102:103]
	v_pk_fma_f32 v[104:105], v[68:69], v[204:205], v[104:105]
	v_pk_fma_f32 v[106:107], v[66:67], v[204:205], v[106:107]
	v_pk_fma_f32 v[108:109], v[64:65], v[204:205], v[108:109]
	v_pk_fma_f32 v[110:111], v[62:63], v[204:205], v[110:111]
	s_waitcnt lgkmcnt(6)
	v_lshlrev_b32_e32 v204, 16, v186
	v_and_b32_e32 v205, 0xffff0000, v186
	v_pk_fma_f32 v[98:99], v[76:77], v[204:205], v[98:99]
	v_pk_fma_f32 v[100:101], v[74:75], v[204:205], v[100:101]
	v_pk_fma_f32 v[102:103], v[72:73], v[204:205], v[102:103]
	v_pk_fma_f32 v[104:105], v[70:71], v[204:205], v[104:105]
	v_pk_fma_f32 v[106:107], v[68:69], v[204:205], v[106:107]
	v_pk_fma_f32 v[108:109], v[66:67], v[204:205], v[108:109]
	v_pk_fma_f32 v[110:111], v[64:65], v[204:205], v[110:111]
	s_waitcnt lgkmcnt(5)
	v_lshlrev_b32_e32 v204, 16, v187
	v_and_b32_e32 v205, 0xffff0000, v187
	v_pk_fma_f32 v[100:101], v[76:77], v[204:205], v[100:101]
	v_pk_fma_f32 v[102:103], v[74:75], v[204:205], v[102:103]
	v_pk_fma_f32 v[104:105], v[72:73], v[204:205], v[104:105]
	v_pk_fma_f32 v[106:107], v[70:71], v[204:205], v[106:107]
	v_pk_fma_f32 v[108:109], v[68:69], v[204:205], v[108:109]
	v_pk_fma_f32 v[110:111], v[66:67], v[204:205], v[110:111]
	s_waitcnt lgkmcnt(4)
	v_lshlrev_b32_e32 v204, 16, v188
	v_and_b32_e32 v205, 0xffff0000, v188
	v_pk_fma_f32 v[102:103], v[76:77], v[204:205], v[102:103]
	v_pk_fma_f32 v[104:105], v[74:75], v[204:205], v[104:105]
	v_pk_fma_f32 v[106:107], v[72:73], v[204:205], v[106:107]
	v_pk_fma_f32 v[108:109], v[70:71], v[204:205], v[108:109]
	v_pk_fma_f32 v[110:111], v[68:69], v[204:205], v[110:111]
	s_waitcnt lgkmcnt(3)
	v_lshlrev_b32_e32 v204, 16, v189
	v_and_b32_e32 v205, 0xffff0000, v189
	v_pk_fma_f32 v[104:105], v[76:77], v[204:205], v[104:105]
	v_pk_fma_f32 v[106:107], v[74:75], v[204:205], v[106:107]
	v_pk_fma_f32 v[108:109], v[72:73], v[204:205], v[108:109]
	v_pk_fma_f32 v[110:111], v[70:71], v[204:205], v[110:111]
	s_waitcnt lgkmcnt(2)
	v_lshlrev_b32_e32 v204, 16, v190
	v_and_b32_e32 v205, 0xffff0000, v190
	v_pk_fma_f32 v[106:107], v[76:77], v[204:205], v[106:107]
	v_pk_fma_f32 v[108:109], v[74:75], v[204:205], v[108:109]
	v_pk_fma_f32 v[110:111], v[72:73], v[204:205], v[110:111]
	s_waitcnt lgkmcnt(1)
	v_lshlrev_b32_e32 v204, 16, v191
	v_and_b32_e32 v205, 0xffff0000, v191
	v_pk_fma_f32 v[108:109], v[76:77], v[204:205], v[108:109]
	v_pk_fma_f32 v[110:111], v[74:75], v[204:205], v[110:111]
	s_waitcnt lgkmcnt(0)
	v_lshlrev_b32_e32 v204, 16, v192
	v_and_b32_e32 v205, 0xffff0000, v192
	v_pk_fma_f32 v[110:111], v[76:77], v[204:205], v[110:111]
	ds_write_b64 v4, v[80:81] offset:0
	ds_write_b64 v4, v[82:83] offset:2048
	ds_write_b64 v4, v[84:85] offset:4096
	ds_write_b64 v4, v[86:87] offset:6144
	ds_write_b64 v4, v[88:89] offset:8192
	ds_write_b64 v4, v[90:91] offset:10240
	ds_write_b64 v4, v[92:93] offset:12288
	ds_write_b64 v4, v[94:95] offset:14336
	ds_write_b64 v4, v[96:97] offset:16384
	ds_write_b64 v4, v[98:99] offset:18432
	ds_write_b64 v4, v[100:101] offset:20480
	ds_write_b64 v4, v[102:103] offset:22528
	ds_write_b64 v4, v[104:105] offset:24576
	ds_write_b64 v4, v[106:107] offset:26624
	ds_write_b64 v4, v[108:109] offset:28672
	ds_write_b64 v4, v[110:111] offset:30720
	s_waitcnt lgkmcnt(0)
	s_barrier
	ds_read_b128 v[80:83], v5 offset:0
	ds_read_b128 v[84:87], v5 offset:16
	ds_read_b128 v[88:91], v5 offset:2048
	ds_read_b128 v[92:95], v5 offset:2064
	ds_read_b128 v[96:99], v5 offset:4096
	ds_read_b128 v[100:103], v5 offset:4112
	ds_read_b128 v[104:107], v5 offset:6144
	ds_read_b128 v[108:111], v5 offset:6160
	s_lshl_b32 s4, s12, 16
	s_lshl_b32 s5, s0, 13
	s_add_u32 s32, s10, s4
	s_addc_u32 s33, s11, 0
	s_add_u32 s32, s32, s5
	s_addc_u32 s33, s33, 0
	s_add_u32 s34, s32, 0x1000
	s_addc_u32 s35, s33, 0
	s_waitcnt lgkmcnt(0)
	v_add_f32_e32 v196, v80, v81
	v_add_f32_e32 v196, v196, v82
	v_add_f32_e32 v196, v196, v83
	v_add_f32_e32 v196, v196, v84
	v_add_f32_e32 v196, v196, v85
	v_add_f32_e32 v196, v196, v86
	v_add_f32_e32 v196, v196, v87
	v_add_f32_e32 v197, v88, v89
	v_add_f32_e32 v197, v197, v90
	v_add_f32_e32 v197, v197, v91
	v_add_f32_e32 v197, v197, v92
	v_add_f32_e32 v197, v197, v93
	v_add_f32_e32 v197, v197, v94
	v_add_f32_e32 v197, v197, v95
	v_add_f32_e32 v198, v96, v97
	v_add_f32_e32 v198, v198, v98
	v_add_f32_e32 v198, v198, v99
	v_add_f32_e32 v198, v198, v100
	v_add_f32_e32 v198, v198, v101
	v_add_f32_e32 v198, v198, v102
	v_add_f32_e32 v198, v198, v103
	v_add_f32_e32 v199, v104, v105
	v_add_f32_e32 v199, v199, v106
	v_add_f32_e32 v199, v199, v107
	v_add_f32_e32 v199, v199, v108
	v_add_f32_e32 v199, v199, v109
	v_add_f32_e32 v199, v199, v110
	v_add_f32_e32 v199, v199, v111
	v_add_f32_dpp v196, v196, v196 quad_perm:[1,0,3,2] row_mask:0xf bank_mask:0xf
	v_add_f32_dpp v197, v197, v197 quad_perm:[1,0,3,2] row_mask:0xf bank_mask:0xf
	v_add_f32_dpp v198, v198, v198 quad_perm:[1,0,3,2] row_mask:0xf bank_mask:0xf
	v_add_f32_dpp v199, v199, v199 quad_perm:[1,0,3,2] row_mask:0xf bank_mask:0xf
	v_add_f32_dpp v196, v196, v196 quad_perm:[2,3,0,1] row_mask:0xf bank_mask:0xf
	v_add_f32_dpp v197, v197, v197 quad_perm:[2,3,0,1] row_mask:0xf bank_mask:0xf
	v_add_f32_dpp v198, v198, v198 quad_perm:[2,3,0,1] row_mask:0xf bank_mask:0xf
	v_add_f32_dpp v199, v199, v199 quad_perm:[2,3,0,1] row_mask:0xf bank_mask:0xf
	v_add_f32_dpp v196, v196, v196 row_half_mirror row_mask:0xf bank_mask:0xf
	v_add_f32_dpp v197, v197, v197 row_half_mirror row_mask:0xf bank_mask:0xf
	v_add_f32_dpp v198, v198, v198 row_half_mirror row_mask:0xf bank_mask:0xf
	v_add_f32_dpp v199, v199, v199 row_half_mirror row_mask:0xf bank_mask:0xf
	v_add_f32_dpp v196, v196, v196 row_mirror row_mask:0xf bank_mask:0xf
	v_add_f32_dpp v197, v197, v197 row_mirror row_mask:0xf bank_mask:0xf
	v_add_f32_dpp v198, v198, v198 row_mirror row_mask:0xf bank_mask:0xf
	v_add_f32_dpp v199, v199, v199 row_mirror row_mask:0xf bank_mask:0xf
	v_add_f32_dpp v196, v196, v196 row_bcast:15 row_mask:0xa bank_mask:0xf
	v_add_f32_dpp v197, v197, v197 row_bcast:15 row_mask:0xa bank_mask:0xf
	v_add_f32_dpp v198, v198, v198 row_bcast:15 row_mask:0xa bank_mask:0xf
	v_add_f32_dpp v199, v199, v199 row_bcast:15 row_mask:0xa bank_mask:0xf
	v_add_f32_dpp v196, v196, v196 row_bcast:31 row_mask:0xc bank_mask:0xf
	v_add_f32_dpp v197, v197, v197 row_bcast:31 row_mask:0xc bank_mask:0xf
	v_add_f32_dpp v198, v198, v198 row_bcast:31 row_mask:0xc bank_mask:0xf
	v_add_f32_dpp v199, v199, v199 row_bcast:31 row_mask:0xc bank_mask:0xf
	v_readlane_b32 s24, v196, 63
	v_readlane_b32 s25, v197, 63
	v_readlane_b32 s26, v198, 63
	v_readlane_b32 s27, v199, 63
	s_nop 0
	v_mul_f32_e32 v200, s24, v8
	v_mul_f32_e32 v201, s25, v8
	v_mul_f32_e32 v202, s26, v8
	v_mul_f32_e32 v203, s27, v8
	v_sub_f32_e32 v80, v80, v200
	v_sub_f32_e32 v81, v81, v200
	v_sub_f32_e32 v82, v82, v200
	v_sub_f32_e32 v83, v83, v200
	v_sub_f32_e32 v84, v84, v200
	v_sub_f32_e32 v85, v85, v200
	v_sub_f32_e32 v86, v86, v200
	v_sub_f32_e32 v87, v87, v200
	v_sub_f32_e32 v88, v88, v201
	v_sub_f32_e32 v89, v89, v201
	v_sub_f32_e32 v90, v90, v201
	v_sub_f32_e32 v91, v91, v201
	v_sub_f32_e32 v92, v92, v201
	v_sub_f32_e32 v93, v93, v201
	v_sub_f32_e32 v94, v94, v201
	v_sub_f32_e32 v95, v95, v201
	v_sub_f32_e32 v96, v96, v202
	v_sub_f32_e32 v97, v97, v202
	v_sub_f32_e32 v98, v98, v202
	v_sub_f32_e32 v99, v99, v202
	v_sub_f32_e32 v100, v100, v202
	v_sub_f32_e32 v101, v101, v202
	v_sub_f32_e32 v102, v102, v202
	v_sub_f32_e32 v103, v103, v202
	v_sub_f32_e32 v104, v104, v203
	v_sub_f32_e32 v105, v105, v203
	v_sub_f32_e32 v106, v106, v203
	v_sub_f32_e32 v107, v107, v203
	v_sub_f32_e32 v108, v108, v203
	v_sub_f32_e32 v109, v109, v203
	v_sub_f32_e32 v110, v110, v203
	v_sub_f32_e32 v111, v111, v203
	v_mul_f32_e32 v196, v80, v80
	v_fmac_f32_e32 v196, v81, v81
	v_fmac_f32_e32 v196, v82, v82
	v_fmac_f32_e32 v196, v83, v83
	v_fmac_f32_e32 v196, v84, v84
	v_fmac_f32_e32 v196, v85, v85
	v_fmac_f32_e32 v196, v86, v86
	v_fmac_f32_e32 v196, v87, v87
	v_mul_f32_e32 v197, v88, v88
	v_fmac_f32_e32 v197, v89, v89
	v_fmac_f32_e32 v197, v90, v90
	v_fmac_f32_e32 v197, v91, v91
	v_fmac_f32_e32 v197, v92, v92
	v_fmac_f32_e32 v197, v93, v93
	v_fmac_f32_e32 v197, v94, v94
	v_fmac_f32_e32 v197, v95, v95
	v_mul_f32_e32 v198, v96, v96
	v_fmac_f32_e32 v198, v97, v97
	v_fmac_f32_e32 v198, v98, v98
	v_fmac_f32_e32 v198, v99, v99
	v_fmac_f32_e32 v198, v100, v100
	v_fmac_f32_e32 v198, v101, v101
	v_fmac_f32_e32 v198, v102, v102
	v_fmac_f32_e32 v198, v103, v103
	v_mul_f32_e32 v199, v104, v104
	v_fmac_f32_e32 v199, v105, v105
	v_fmac_f32_e32 v199, v106, v106
	v_fmac_f32_e32 v199, v107, v107
	v_fmac_f32_e32 v199, v108, v108
	v_fmac_f32_e32 v199, v109, v109
	v_fmac_f32_e32 v199, v110, v110
	v_fmac_f32_e32 v199, v111, v111
	v_add_f32_dpp v196, v196, v196 quad_perm:[1,0,3,2] row_mask:0xf bank_mask:0xf
	v_add_f32_dpp v197, v197, v197 quad_perm:[1,0,3,2] row_mask:0xf bank_mask:0xf
	v_add_f32_dpp v198, v198, v198 quad_perm:[1,0,3,2] row_mask:0xf bank_mask:0xf
	v_add_f32_dpp v199, v199, v199 quad_perm:[1,0,3,2] row_mask:0xf bank_mask:0xf
	v_add_f32_dpp v196, v196, v196 quad_perm:[2,3,0,1] row_mask:0xf bank_mask:0xf
	v_add_f32_dpp v197, v197, v197 quad_perm:[2,3,0,1] row_mask:0xf bank_mask:0xf
	v_add_f32_dpp v198, v198, v198 quad_perm:[2,3,0,1] row_mask:0xf bank_mask:0xf
	v_add_f32_dpp v199, v199, v199 quad_perm:[2,3,0,1] row_mask:0xf bank_mask:0xf
	v_add_f32_dpp v196, v196, v196 row_half_mirror row_mask:0xf bank_mask:0xf
	v_add_f32_dpp v197, v197, v197 row_half_mirror row_mask:0xf bank_mask:0xf
	v_add_f32_dpp v198, v198, v198 row_half_mirror row_mask:0xf bank_mask:0xf
	v_add_f32_dpp v199, v199, v199 row_half_mirror row_mask:0xf bank_mask:0xf
	v_add_f32_dpp v196, v196, v196 row_mirror row_mask:0xf bank_mask:0xf
	v_add_f32_dpp v197, v197, v197 row_mirror row_mask:0xf bank_mask:0xf
	v_add_f32_dpp v198, v198, v198 row_mirror row_mask:0xf bank_mask:0xf
	v_add_f32_dpp v199, v199, v199 row_mirror row_mask:0xf bank_mask:0xf
	v_add_f32_dpp v196, v196, v196 row_bcast:15 row_mask:0xa bank_mask:0xf
	v_add_f32_dpp v197, v197, v197 row_bcast:15 row_mask:0xa bank_mask:0xf
	v_add_f32_dpp v198, v198, v198 row_bcast:15 row_mask:0xa bank_mask:0xf
	v_add_f32_dpp v199, v199, v199 row_bcast:15 row_mask:0xa bank_mask:0xf
	v_add_f32_dpp v196, v196, v196 row_bcast:31 row_mask:0xc bank_mask:0xf
	v_add_f32_dpp v197, v197, v197 row_bcast:31 row_mask:0xc bank_mask:0xf
	v_add_f32_dpp v198, v198, v198 row_bcast:31 row_mask:0xc bank_mask:0xf
	v_add_f32_dpp v199, v199, v199 row_bcast:31 row_mask:0xc bank_mask:0xf
	v_readlane_b32 s24, v196, 63
	v_readlane_b32 s25, v197, 63
	v_readlane_b32 s26, v198, 63
	v_readlane_b32 s27, v199, 63
	s_nop 0
	v_fma_f32 v200, s24, v8, v9
	v_fma_f32 v201, s25, v8, v9
	v_fma_f32 v202, s26, v8, v9
	v_fma_f32 v203, s27, v8, v9
	v_rsq_f32_e32 v200, v200
	v_rsq_f32_e32 v201, v201
	v_rsq_f32_e32 v202, v202
	v_rsq_f32_e32 v203, v203
	s_nop 0
	v_mul_f32_e32 v80, v80, v200
	v_mul_f32_e32 v81, v81, v200
	v_mul_f32_e32 v82, v82, v200
	v_mul_f32_e32 v83, v83, v200
	v_mul_f32_e32 v84, v84, v200
	v_mul_f32_e32 v85, v85, v200
	v_mul_f32_e32 v86, v86, v200
	v_mul_f32_e32 v87, v87, v200
	v_fma_f32 v80, v80, v224, v232
	v_fma_f32 v81, v81, v225, v233
	v_fma_f32 v82, v82, v226, v234
	v_fma_f32 v83, v83, v227, v235
	v_fma_f32 v84, v84, v228, v236
	v_fma_f32 v85, v85, v229, v237
	v_fma_f32 v86, v86, v230, v238
	v_fma_f32 v87, v87, v231, v239
	v_mul_f32_e32 v88, v88, v201
	v_mul_f32_e32 v89, v89, v201
	v_mul_f32_e32 v90, v90, v201
	v_mul_f32_e32 v91, v91, v201
	v_mul_f32_e32 v92, v92, v201
	v_mul_f32_e32 v93, v93, v201
	v_mul_f32_e32 v94, v94, v201
	v_mul_f32_e32 v95, v95, v201
	v_fma_f32 v88, v88, v224, v232
	v_fma_f32 v89, v89, v225, v233
	v_fma_f32 v90, v90, v226, v234
	v_fma_f32 v91, v91, v227, v235
	v_fma_f32 v92, v92, v228, v236
	v_fma_f32 v93, v93, v229, v237
	v_fma_f32 v94, v94, v230, v238
	v_fma_f32 v95, v95, v231, v239
	v_mul_f32_e32 v96, v96, v202
	v_mul_f32_e32 v97, v97, v202
	v_mul_f32_e32 v98, v98, v202
	v_mul_f32_e32 v99, v99, v202
	v_mul_f32_e32 v100, v100, v202
	v_mul_f32_e32 v101, v101, v202
	v_mul_f32_e32 v102, v102, v202
	v_mul_f32_e32 v103, v103, v202
	v_fma_f32 v96, v96, v224, v232
	v_fma_f32 v97, v97, v225, v233
	v_fma_f32 v98, v98, v226, v234
	v_fma_f32 v99, v99, v227, v235
	v_fma_f32 v100, v100, v228, v236
	v_fma_f32 v101, v101, v229, v237
	v_fma_f32 v102, v102, v230, v238
	v_fma_f32 v103, v103, v231, v239
	v_mul_f32_e32 v104, v104, v203
	v_mul_f32_e32 v105, v105, v203
	v_mul_f32_e32 v106, v106, v203
	v_mul_f32_e32 v107, v107, v203
	v_mul_f32_e32 v108, v108, v203
	v_mul_f32_e32 v109, v109, v203
	v_mul_f32_e32 v110, v110, v203
	v_mul_f32_e32 v111, v111, v203
	v_fma_f32 v104, v104, v224, v232
	v_fma_f32 v105, v105, v225, v233
	v_fma_f32 v106, v106, v226, v234
	v_fma_f32 v107, v107, v227, v235
	v_fma_f32 v108, v108, v228, v236
	v_fma_f32 v109, v109, v229, v237
	v_fma_f32 v110, v110, v230, v238
	v_fma_f32 v111, v111, v231, v239
	v_mul_f32_e32 v160, v80, v11
	v_mul_f32_e32 v161, v81, v11
	v_mul_f32_e32 v162, v82, v11
	v_mul_f32_e32 v163, v83, v11
	v_mul_f32_e32 v164, v84, v11
	v_mul_f32_e32 v165, v85, v11
	v_mul_f32_e32 v166, v86, v11
	v_mul_f32_e32 v167, v87, v11
	v_exp_f32_e32 v160, v160
	v_exp_f32_e32 v161, v161
	v_exp_f32_e32 v162, v162
	v_exp_f32_e32 v163, v163
	v_exp_f32_e32 v164, v164
	v_exp_f32_e32 v165, v165
	v_exp_f32_e32 v166, v166
	v_exp_f32_e32 v167, v167
	s_nop 0
	v_add_f32_e32 v160, v160, v13
	v_add_f32_e32 v161, v161, v13
	v_add_f32_e32 v162, v162, v13
	v_add_f32_e32 v163, v163, v13
	v_add_f32_e32 v164, v164, v13
	v_add_f32_e32 v165, v165, v13
	v_add_f32_e32 v166, v166, v13
	v_add_f32_e32 v167, v167, v13
	v_rcp_f32_e32 v160, v160
	v_rcp_f32_e32 v161, v161
	v_rcp_f32_e32 v162, v162
	v_rcp_f32_e32 v163, v163
	v_rcp_f32_e32 v164, v164
	v_rcp_f32_e32 v165, v165
	v_rcp_f32_e32 v166, v166
	v_rcp_f32_e32 v167, v167
	s_nop 0
	v_mul_f32_e32 v80, v80, v160
	v_mul_f32_e32 v81, v81, v161
	v_mul_f32_e32 v82, v82, v162
	v_mul_f32_e32 v83, v83, v163
	v_mul_f32_e32 v84, v84, v164
	v_mul_f32_e32 v85, v85, v165
	v_mul_f32_e32 v86, v86, v166
	v_mul_f32_e32 v87, v87, v167
	v_cvt_pk_bf16_f32 v208, v80, v81
	v_cvt_pk_bf16_f32 v209, v82, v83
	v_cvt_pk_bf16_f32 v210, v84, v85
	v_cvt_pk_bf16_f32 v211, v86, v87
	global_store_dwordx4 v7, v[208:211], s[32:33] offset:0
	v_mul_f32_e32 v160, v88, v11
	v_mul_f32_e32 v161, v89, v11
	v_mul_f32_e32 v162, v90, v11
	v_mul_f32_e32 v163, v91, v11
	v_mul_f32_e32 v164, v92, v11
	v_mul_f32_e32 v165, v93, v11
	v_mul_f32_e32 v166, v94, v11
	v_mul_f32_e32 v167, v95, v11
	v_exp_f32_e32 v160, v160
	v_exp_f32_e32 v161, v161
	v_exp_f32_e32 v162, v162
	v_exp_f32_e32 v163, v163
	v_exp_f32_e32 v164, v164
	v_exp_f32_e32 v165, v165
	v_exp_f32_e32 v166, v166
	v_exp_f32_e32 v167, v167
	s_nop 0
	v_add_f32_e32 v160, v160, v13
	v_add_f32_e32 v161, v161, v13
	v_add_f32_e32 v162, v162, v13
	v_add_f32_e32 v163, v163, v13
	v_add_f32_e32 v164, v164, v13
	v_add_f32_e32 v165, v165, v13
	v_add_f32_e32 v166, v166, v13
	v_add_f32_e32 v167, v167, v13
	v_rcp_f32_e32 v160, v160
	v_rcp_f32_e32 v161, v161
	v_rcp_f32_e32 v162, v162
	v_rcp_f32_e32 v163, v163
	v_rcp_f32_e32 v164, v164
	v_rcp_f32_e32 v165, v165
	v_rcp_f32_e32 v166, v166
	v_rcp_f32_e32 v167, v167
	s_nop 0
	v_mul_f32_e32 v88, v88, v160
	v_mul_f32_e32 v89, v89, v161
	v_mul_f32_e32 v90, v90, v162
	v_mul_f32_e32 v91, v91, v163
	v_mul_f32_e32 v92, v92, v164
	v_mul_f32_e32 v93, v93, v165
	v_mul_f32_e32 v94, v94, v166
	v_mul_f32_e32 v95, v95, v167
	v_cvt_pk_bf16_f32 v240, v88, v89
	v_cvt_pk_bf16_f32 v241, v90, v91
	v_cvt_pk_bf16_f32 v242, v92, v93
	v_cvt_pk_bf16_f32 v243, v94, v95
	global_store_dwordx4 v7, v[240:243], s[32:33] offset:2048
	v_mul_f32_e32 v160, v96, v11
	v_mul_f32_e32 v161, v97, v11
	v_mul_f32_e32 v162, v98, v11
	v_mul_f32_e32 v163, v99, v11
	v_mul_f32_e32 v164, v100, v11
	v_mul_f32_e32 v165, v101, v11
	v_mul_f32_e32 v166, v102, v11
	v_mul_f32_e32 v167, v103, v11
	v_exp_f32_e32 v160, v160
	v_exp_f32_e32 v161, v161
	v_exp_f32_e32 v162, v162
	v_exp_f32_e32 v163, v163
	v_exp_f32_e32 v164, v164
	v_exp_f32_e32 v165, v165
	v_exp_f32_e32 v166, v166
	v_exp_f32_e32 v167, v167
	s_nop 0
	v_add_f32_e32 v160, v160, v13
	v_add_f32_e32 v161, v161, v13
	v_add_f32_e32 v162, v162, v13
	v_add_f32_e32 v163, v163, v13
	v_add_f32_e32 v164, v164, v13
	v_add_f32_e32 v165, v165, v13
	v_add_f32_e32 v166, v166, v13
	v_add_f32_e32 v167, v167, v13
	v_rcp_f32_e32 v160, v160
	v_rcp_f32_e32 v161, v161
	v_rcp_f32_e32 v162, v162
	v_rcp_f32_e32 v163, v163
	v_rcp_f32_e32 v164, v164
	v_rcp_f32_e32 v165, v165
	v_rcp_f32_e32 v166, v166
	v_rcp_f32_e32 v167, v167
	s_nop 0
	v_mul_f32_e32 v96, v96, v160
	v_mul_f32_e32 v97, v97, v161
	v_mul_f32_e32 v98, v98, v162
	v_mul_f32_e32 v99, v99, v163
	v_mul_f32_e32 v100, v100, v164
	v_mul_f32_e32 v101, v101, v165
	v_mul_f32_e32 v102, v102, v166
	v_mul_f32_e32 v103, v103, v167
	v_cvt_pk_bf16_f32 v148, v96, v97
	v_cvt_pk_bf16_f32 v149, v98, v99
	v_cvt_pk_bf16_f32 v150, v100, v101
	v_cvt_pk_bf16_f32 v151, v102, v103
	global_store_dwordx4 v7, v[148:151], s[34:35] offset:0
	v_mul_f32_e32 v160, v104, v11
	v_mul_f32_e32 v161, v105, v11
	v_mul_f32_e32 v162, v106, v11
	v_mul_f32_e32 v163, v107, v11
	v_mul_f32_e32 v164, v108, v11
	v_mul_f32_e32 v165, v109, v11
	v_mul_f32_e32 v166, v110, v11
	v_mul_f32_e32 v167, v111, v11
	v_exp_f32_e32 v160, v160
	v_exp_f32_e32 v161, v161
	v_exp_f32_e32 v162, v162
	v_exp_f32_e32 v163, v163
	v_exp_f32_e32 v164, v164
	v_exp_f32_e32 v165, v165
	v_exp_f32_e32 v166, v166
	v_exp_f32_e32 v167, v167
	s_nop 0
	v_add_f32_e32 v160, v160, v13
	v_add_f32_e32 v161, v161, v13
	v_add_f32_e32 v162, v162, v13
	v_add_f32_e32 v163, v163, v13
	v_add_f32_e32 v164, v164, v13
	v_add_f32_e32 v165, v165, v13
	v_add_f32_e32 v166, v166, v13
	v_add_f32_e32 v167, v167, v13
	v_rcp_f32_e32 v160, v160
	v_rcp_f32_e32 v161, v161
	v_rcp_f32_e32 v162, v162
	v_rcp_f32_e32 v163, v163
	v_rcp_f32_e32 v164, v164
	v_rcp_f32_e32 v165, v165
	v_rcp_f32_e32 v166, v166
	v_rcp_f32_e32 v167, v167
	s_nop 0
	v_mul_f32_e32 v104, v104, v160
	v_mul_f32_e32 v105, v105, v161
	v_mul_f32_e32 v106, v106, v162
	v_mul_f32_e32 v107, v107, v163
	v_mul_f32_e32 v108, v108, v164
	v_mul_f32_e32 v109, v109, v165
	v_mul_f32_e32 v110, v110, v166
	v_mul_f32_e32 v111, v111, v167
	v_cvt_pk_bf16_f32 v152, v104, v105
	v_cvt_pk_bf16_f32 v153, v106, v107
	v_cvt_pk_bf16_f32 v154, v108, v109
	v_cvt_pk_bf16_f32 v155, v110, v111
	global_store_dwordx4 v7, v[152:155], s[34:35] offset:2048
	s_add_i32 s12, s12, s66
	s_cmp_lt_i32 s12, 0x400
	s_cbranch_scc1 .Lcv_loop

	.amdhsa_kernel _Z10fwd_kernel6Params
		.amdhsa_group_segment_fixed_size 0
		.amdhsa_private_segment_fixed_size 0
		.amdhsa_kernarg_size 440
		.amdhsa_user_sgpr_count 2
		.amdhsa_user_sgpr_dispatch_ptr 0
		.amdhsa_user_sgpr_queue_ptr 0
		.amdhsa_user_sgpr_kernarg_segment_ptr 1
		.amdhsa_user_sgpr_dispatch_id 0
		.amdhsa_user_sgpr_kernarg_preload_length 0
		.amdhsa_user_sgpr_kernarg_preload_offset 0
		.amdhsa_user_sgpr_private_segment_size 0
		.amdhsa_uses_dynamic_stack 0
		.amdhsa_enable_private_segment 0
		.amdhsa_system_sgpr_workgroup_id_x 1
		.amdhsa_system_sgpr_workgroup_id_y 0
		.amdhsa_system_sgpr_workgroup_id_z 0
		.amdhsa_system_sgpr_workgroup_info 0
		.amdhsa_system_vgpr_workitem_id 2
		.amdhsa_next_free_vgpr 248
		.amdhsa_next_free_sgpr 102
		.amdhsa_accum_offset 248
		.amdhsa_reserve_vcc 1
		.amdhsa_float_round_mode_32 0
		.amdhsa_float_round_mode_16_64 0
		.amdhsa_float_denorm_mode_32 3
		.amdhsa_float_denorm_mode_16_64 3
		.amdhsa_dx10_clamp 1
		.amdhsa_ieee_mode 1
		.amdhsa_fp16_overflow 0
		.amdhsa_tg_split 0
		.amdhsa_exception_fp_ieee_invalid_op 0
		.amdhsa_exception_fp_denorm_src 0
		.amdhsa_exception_fp_ieee_div_zero 0
		.amdhsa_exception_fp_ieee_overflow 0
		.amdhsa_exception_fp_ieee_underflow 0
		.amdhsa_exception_fp_ieee_inexact 0
		.amdhsa_exception_int_div_zero 0
	.end_amdhsa_kernel

.Lfunc_end0:
	.size	_Z10fwd_kernel6Params, .Lfunc_end0-_Z10fwd_kernel6Params
	.set _Z10fwd_kernel6Params.num_vgpr, 248
	.set _Z10fwd_kernel6Params.num_agpr, 0
	.set _Z10fwd_kernel6Params.numbered_sgpr, 102
	.set _Z10fwd_kernel6Params.num_named_barrier, 0
	.set _Z10fwd_kernel6Params.private_seg_size, 0
	.set _Z10fwd_kernel6Params.uses_vcc, 1
	.set _Z10fwd_kernel6Params.uses_flat_scratch, 0
	.set _Z10fwd_kernel6Params.has_dyn_sized_stack, 0
	.set _Z10fwd_kernel6Params.has_recursion, 0
	.set _Z10fwd_kernel6Params.has_indirect_call, 0

amdhsa.kernels:
  - .agpr_count:     0
    .args:
      - .offset:         0
        .size:           184
        .value_kind:     by_value
      - .offset:         184
        .size:           4
        .value_kind:     hidden_block_count_x
      - .offset:         188
        .size:           4
        .value_kind:     hidden_block_count_y
      - .offset:         192
        .size:           4
        .value_kind:     hidden_block_count_z
      - .offset:         196
        .size:           2
        .value_kind:     hidden_group_size_x
      - .offset:         198
        .size:           2
        .value_kind:     hidden_group_size_y
      - .offset:         200
        .size:           2
        .value_kind:     hidden_group_size_z
      - .offset:         202
        .size:           2
        .value_kind:     hidden_remainder_x
      - .offset:         204
        .size:           2
        .value_kind:     hidden_remainder_y
      - .offset:         206
        .size:           2
        .value_kind:     hidden_remainder_z
      - .offset:         224
        .size:           8
        .value_kind:     hidden_global_offset_x
      - .offset:         232
        .size:           8
        .value_kind:     hidden_global_offset_y
      - .offset:         240
        .size:           8
        .value_kind:     hidden_global_offset_z
      - .offset:         248
        .size:           2
        .value_kind:     hidden_grid_dims
      - .offset:         272
        .size:           8
        .value_kind:     hidden_multigrid_sync_arg
      - .offset:         304
        .size:           4
        .value_kind:     hidden_dynamic_lds_size
    .group_segment_fixed_size: 0
    .kernarg_segment_align: 8
    .kernarg_segment_size: 440
    .language:       OpenCL C
    .language_version:
      - 2
      - 0
    .max_flat_workgroup_size: 512
    .name:           _Z10fwd_kernel6Params
    .private_segment_fixed_size: 0
    .sgpr_count:     108
    .sgpr_spill_count: 326
    .symbol:         _Z10fwd_kernel6Params.kd
    .uniform_work_group_size: 1
    .uses_dynamic_stack: false
    .vgpr_count:     248
    .vgpr_spill_count: 0
    .wavefront_size: 64
